# gla_scan: next-batch loads prefetched into a second register set (double buffering), counted vmcnt
# baseline (speedup 1.0000x reference)
.LBB0_1681:
	v_ashrrev_i32_e32 v0, 7, v28
	v_and_b32_e32 v0, 0xffffff80, v0
	v_ashrrev_i32_e32 v1, 31, v0
	v_and_b32_e32 v4, 0x3fff, v29
	v_lshlrev_b64 v[2:3], 18, v[0:1]
	v_lshl_or_b32 v2, v4, 4, v2
	v_lshlrev_b64 v[0:1], 10, v[0:1]
	v_lshl_add_u64 v[16:17], s[6:7], 0, v[2:3]
	v_lshl_add_u64 v[18:19], v[14:15], 0, v[0:1]
	s_mov_b32 s17, -4
	v_mov_b32_e32 v20, 0
	v_mov_b32_e32 v24, 0
	v_mov_b32_e32 v21, v13
	v_mov_b32_e32 v25, v13
	v_mov_b32_e32 v22, 0
	v_mov_b32_e32 v26, 0
	v_mov_b32_e32 v23, v13
	v_mov_b32_e32 v27, v13
	global_load_dwordx4 v[76:79], v[18:19], off offset:-3072
	global_load_dwordx4 v[80:83], v[18:19], off offset:-3088
	global_load_dwordx4 v[88:91], v[18:19], off offset:-2048
	global_load_dwordx4 v[92:95], v[18:19], off offset:-2064
	global_load_dwordx4 v[96:99], v[18:19], off offset:-1024
	global_load_dwordx4 v[100:103], v[18:19], off offset:-1040
	global_load_dwordx4 v[112:115], v[18:19], off
	global_load_dwordx4 v[116:119], v[18:19], off offset:-16
	v_add_co_u32_e32 v124, vcc, 0xfff40000, v16
	s_nop 1
	v_addc_co_u32_e32 v125, vcc, -1, v17, vcc
	global_load_dwordx4 v[84:87], v[124:125], off
	s_mov_b64 s[98:99], 0x40000
	v_lshl_add_u64 v[126:127], v[124:125], 0, s[98:99]
	global_load_dwordx4 v[104:107], v[126:127], off
	s_mov_b64 s[100:101], 0x80000
	v_lshl_add_u64 v[128:129], v[124:125], 0, s[100:101]
	global_load_dwordx4 v[120:123], v[128:129], off
	global_load_dwordx4 v[108:111], v[16:17], off
	s_waitcnt vmcnt(0)
.LBB0_1682:
	v_add_co_u32_e32 v70, vcc, 0xfff40000, v16
	v_bfe_u32 v63, v21, 16, 1
	s_nop 0
	v_addc_co_u32_e32 v71, vcc, -1, v17, vcc
	v_add_co_u32_e32 v72, vcc, 0xfff80000, v16
	v_bfe_u32 v65, v22, 16, 1
	s_nop 0
	v_addc_co_u32_e32 v73, vcc, -1, v17, vcc
	v_bfe_u32 v67, v23, 16, 1
	v_bfe_u32 v64, v25, 16, 1
	v_bfe_u32 v66, v26, 16, 1
	v_bfe_u32 v68, v27, 16, 1
	v_add3_u32 v63, v21, v63, s14
	v_add3_u32 v65, v22, v65, s14
	v_add3_u32 v67, v23, v67, s14
	v_add_co_u32_e32 v74, vcc, 0xfffc0000, v16
	v_add3_u32 v64, v25, v64, s14
	v_add3_u32 v66, v26, v66, s14
	v_add3_u32 v68, v27, v68, s14
	v_lshrrev_b32_e32 v63, 16, v63
	v_lshrrev_b32_e32 v65, 16, v65
	v_lshrrev_b32_e32 v67, 16, v67
	v_addc_co_u32_e32 v75, vcc, -1, v17, vcc
	v_and_or_b32 v63, v64, s15, v63
	v_and_or_b32 v64, v66, s15, v65
	v_and_or_b32 v65, v68, s15, v67
	v_bfe_u32 v12, v20, 16, 1
	v_bfe_u32 v62, v24, 16, 1
	v_add3_u32 v12, v20, v12, s14
	v_add3_u32 v62, v24, v62, s14
	v_lshrrev_b32_e32 v12, 16, v12
	v_and_or_b32 v62, v62, s15, v12
	global_store_dwordx4 v[70:71], v[62:65], off
	s_add_i32 s17, s17, 4
	v_lshl_add_u64 v[18:19], v[18:19], 0, s[12:13]
	s_cmpk_gt_u32 s17, 0x7b
	s_waitcnt vmcnt(4)
	v_mov_b32_e32 v30, v76
	v_mov_b32_e32 v31, v77
	v_mov_b32_e32 v32, v78
	v_mov_b32_e32 v33, v79
	v_mov_b32_e32 v34, v80
	v_mov_b32_e32 v35, v81
	v_mov_b32_e32 v36, v82
	v_mov_b32_e32 v37, v83
	v_mov_b32_e32 v38, v84
	v_mov_b32_e32 v39, v85
	v_mov_b32_e32 v40, v86
	v_mov_b32_e32 v41, v87
	v_mov_b32_e32 v42, v88
	v_mov_b32_e32 v43, v89
	v_mov_b32_e32 v44, v90
	v_mov_b32_e32 v45, v91
	v_mov_b32_e32 v46, v92
	v_mov_b32_e32 v47, v93
	v_mov_b32_e32 v48, v94
	v_mov_b32_e32 v49, v95
	v_mov_b32_e32 v50, v96
	v_mov_b32_e32 v51, v97
	v_mov_b32_e32 v52, v98
	v_mov_b32_e32 v53, v99
	v_mov_b32_e32 v54, v100
	v_mov_b32_e32 v55, v101
	v_mov_b32_e32 v56, v102
	v_mov_b32_e32 v57, v103
	v_mov_b32_e32 v58, v104
	v_mov_b32_e32 v59, v105
	v_mov_b32_e32 v60, v106
	v_mov_b32_e32 v61, v107
	v_mov_b32_e32 v4, v108
	v_mov_b32_e32 v5, v109
	v_mov_b32_e32 v6, v110
	v_mov_b32_e32 v7, v111
	v_mov_b32_e32 v0, v112
	v_mov_b32_e32 v1, v113
	v_mov_b32_e32 v2, v114
	v_mov_b32_e32 v3, v115
	v_mov_b32_e32 v8, v116
	v_mov_b32_e32 v9, v117
	v_mov_b32_e32 v10, v118
	v_mov_b32_e32 v11, v119
	v_mov_b32_e32 v66, v120
	v_mov_b32_e32 v67, v121
	v_mov_b32_e32 v68, v122
	v_mov_b32_e32 v69, v123
	s_cbranch_scc1 .Lgs_skip
	global_load_dwordx4 v[76:79], v[18:19], off offset:-3072
	global_load_dwordx4 v[80:83], v[18:19], off offset:-3088
	global_load_dwordx4 v[88:91], v[18:19], off offset:-2048
	global_load_dwordx4 v[92:95], v[18:19], off offset:-2064
	global_load_dwordx4 v[96:99], v[18:19], off offset:-1024
	global_load_dwordx4 v[100:103], v[18:19], off offset:-1040
	global_load_dwordx4 v[112:115], v[18:19], off
	global_load_dwordx4 v[116:119], v[18:19], off offset:-16
	s_mov_b64 s[98:99], 0x40000
	v_lshl_add_u64 v[124:125], v[16:17], 0, s[98:99]
	global_load_dwordx4 v[84:87], v[124:125], off
	s_mov_b64 s[100:101], 0x80000
	v_lshl_add_u64 v[126:127], v[16:17], 0, s[100:101]
	global_load_dwordx4 v[104:107], v[126:127], off
	s_mov_b64 s[98:99], 0xc0000
	v_lshl_add_u64 v[128:129], v[16:17], 0, s[98:99]
	global_load_dwordx4 v[120:123], v[128:129], off
	v_lshl_add_u64 v[130:131], v[16:17], 0, s[10:11]
	global_load_dwordx4 v[108:111], v[130:131], off
.Lgs_skip:
	v_mov_b32_e32 v62, v34
	v_mov_b32_e32 v63, v36
	v_mov_b32_e32 v36, v35
	v_mov_b32_e32 v34, v30
	v_mov_b32_e32 v35, v32
	v_mov_b32_e32 v32, v31
	v_lshlrev_b32_e32 v31, 16, v39
	v_lshlrev_b32_e32 v30, 16, v38
	v_and_b32_e32 v39, 0xffff0000, v39
	v_and_b32_e32 v38, 0xffff0000, v38
	v_lshlrev_b32_e32 v65, 16, v41
	v_lshlrev_b32_e32 v64, 16, v40
	v_and_b32_e32 v41, 0xffff0000, v41
	v_and_b32_e32 v40, 0xffff0000, v40
	v_pk_fma_f32 v[30:31], v[20:21], v[62:63], v[30:31]
	v_pk_fma_f32 v[24:25], v[24:25], v[36:37], v[38:39]
	v_pk_fma_f32 v[34:35], v[22:23], v[34:35], v[64:65]
	v_pk_fma_f32 v[26:27], v[26:27], v[32:33], v[40:41]
	v_bfe_u32 v22, v24, 16, 1
	v_bfe_u32 v23, v30, 16, 1
	v_bfe_u32 v32, v31, 16, 1
	v_bfe_u32 v33, v34, 16, 1
	v_bfe_u32 v36, v35, 16, 1
	v_bfe_u32 v12, v27, 16, 1
	v_bfe_u32 v20, v26, 16, 1
	v_bfe_u32 v21, v25, 16, 1
	v_add3_u32 v37, v24, v22, s14
	v_add3_u32 v22, v35, v36, s14
	v_add3_u32 v33, v34, v33, s14
	v_add3_u32 v32, v31, v32, s14
	v_add3_u32 v23, v30, v23, s14
	v_add3_u32 v21, v25, v21, s14
	v_add3_u32 v20, v26, v20, s14
	v_add3_u32 v12, v27, v12, s14
	v_lshrrev_b32_e32 v36, 16, v23
	v_lshrrev_b32_e32 v32, 16, v32
	v_lshrrev_b32_e32 v33, 16, v33
	v_lshrrev_b32_e32 v22, 16, v22
	v_and_or_b32 v23, v12, s15, v22
	v_and_or_b32 v22, v20, s15, v33
	v_and_or_b32 v21, v21, s15, v32
	v_and_or_b32 v20, v37, s15, v36
	global_store_dwordx4 v[72:73], v[20:23], off
	s_nop 1
	v_mov_b32_e32 v20, v46
	v_mov_b32_e32 v21, v48
	v_lshlrev_b32_e32 v23, 16, v59
	v_lshlrev_b32_e32 v22, 16, v58
	v_pk_fma_f32 v[30:31], v[30:31], v[20:21], v[22:23]
	v_mov_b32_e32 v48, v47
	v_and_b32_e32 v21, 0xffff0000, v59
	v_and_b32_e32 v20, 0xffff0000, v58
	v_pk_fma_f32 v[24:25], v[24:25], v[48:49], v[20:21]
	v_mov_b32_e32 v20, v42
	v_mov_b32_e32 v21, v44
	v_lshlrev_b32_e32 v23, 16, v61
	v_lshlrev_b32_e32 v22, 16, v60
	v_pk_fma_f32 v[32:33], v[34:35], v[20:21], v[22:23]
	v_mov_b32_e32 v44, v43
	v_and_b32_e32 v21, 0xffff0000, v61
	v_and_b32_e32 v20, 0xffff0000, v60
	v_bfe_u32 v22, v24, 16, 1
	v_pk_fma_f32 v[26:27], v[26:27], v[44:45], v[20:21]
	v_add3_u32 v34, v24, v22, s14
	v_bfe_u32 v22, v30, 16, 1
	v_bfe_u32 v23, v31, 16, 1
	v_bfe_u32 v35, v32, 16, 1
	v_bfe_u32 v36, v33, 16, 1
	v_bfe_u32 v12, v27, 16, 1
	v_bfe_u32 v20, v26, 16, 1
	v_bfe_u32 v21, v25, 16, 1
	v_add3_u32 v36, v33, v36, s14
	v_add3_u32 v35, v32, v35, s14
	v_add3_u32 v23, v31, v23, s14
	v_add3_u32 v22, v30, v22, s14
	v_add3_u32 v21, v25, v21, s14
	v_add3_u32 v20, v26, v20, s14
	v_add3_u32 v12, v27, v12, s14
	v_lshrrev_b32_e32 v37, 16, v22
	v_lshrrev_b32_e32 v38, 16, v23
	v_lshrrev_b32_e32 v22, 16, v35
	v_lshrrev_b32_e32 v23, 16, v36
	v_and_or_b32 v23, v12, s15, v23
	v_and_or_b32 v22, v20, s15, v22
	v_and_or_b32 v21, v21, s15, v38
	v_and_or_b32 v20, v34, s15, v37
	global_store_dwordx4 v[74:75], v[20:23], off
	s_nop 1
	v_mov_b32_e32 v20, v54
	v_mov_b32_e32 v21, v56
	v_lshlrev_b32_e32 v23, 16, v67
	v_lshlrev_b32_e32 v22, 16, v66
	v_pk_fma_f32 v[30:31], v[30:31], v[20:21], v[22:23]
	v_mov_b32_e32 v56, v55
	v_and_b32_e32 v21, 0xffff0000, v67
	v_and_b32_e32 v20, 0xffff0000, v66
	v_pk_fma_f32 v[24:25], v[24:25], v[56:57], v[20:21]
	v_mov_b32_e32 v20, v50
	v_mov_b32_e32 v21, v52
	v_lshlrev_b32_e32 v23, 16, v69
	v_lshlrev_b32_e32 v22, 16, v68
	v_pk_fma_f32 v[32:33], v[32:33], v[20:21], v[22:23]
	v_mov_b32_e32 v52, v51
	v_and_b32_e32 v21, 0xffff0000, v69
	v_and_b32_e32 v20, 0xffff0000, v68
	v_bfe_u32 v22, v24, 16, 1
	v_pk_fma_f32 v[26:27], v[26:27], v[52:53], v[20:21]
	v_add3_u32 v34, v24, v22, s14
	v_bfe_u32 v22, v30, 16, 1
	v_bfe_u32 v23, v31, 16, 1
	v_bfe_u32 v35, v32, 16, 1
	v_bfe_u32 v36, v33, 16, 1
	v_bfe_u32 v12, v27, 16, 1
	v_bfe_u32 v20, v26, 16, 1
	v_bfe_u32 v21, v25, 16, 1
	v_add3_u32 v36, v33, v36, s14
	v_add3_u32 v35, v32, v35, s14
	v_add3_u32 v23, v31, v23, s14
	v_add3_u32 v22, v30, v22, s14
	v_add3_u32 v21, v25, v21, s14
	v_add3_u32 v20, v26, v20, s14
	v_add3_u32 v12, v27, v12, s14
	v_lshrrev_b32_e32 v37, 16, v22
	v_lshrrev_b32_e32 v38, 16, v23
	v_lshrrev_b32_e32 v22, 16, v35
	v_lshrrev_b32_e32 v23, 16, v36
	v_and_or_b32 v23, v12, s15, v23
	v_and_or_b32 v22, v20, s15, v22
	v_and_or_b32 v21, v21, s15, v38
	v_and_or_b32 v20, v34, s15, v37
	global_store_dwordx4 v[16:17], v[20:23], off
	v_lshl_add_u64 v[16:17], v[16:17], 0, s[10:11]
	s_nop 0
	v_mov_b32_e32 v20, v30
	v_mov_b32_e32 v21, v24
	v_lshlrev_b32_e32 v22, 16, v4
	v_and_b32_e32 v23, 0xffff0000, v4
	v_mov_b32_e32 v24, v31
	v_lshlrev_b32_e32 v4, 16, v5
	v_and_b32_e32 v5, 0xffff0000, v5
	v_pk_fma_f32 v[20:21], v[20:21], v[8:9], v[22:23]
	v_pk_fma_f32 v[4:5], v[24:25], v[10:11], v[4:5]
	v_mov_b32_e32 v8, v32
	v_mov_b32_e32 v9, v26
	v_lshlrev_b32_e32 v10, 16, v6
	v_and_b32_e32 v11, 0xffff0000, v6
	v_pk_fma_f32 v[22:23], v[8:9], v[0:1], v[10:11]
	v_mov_b32_e32 v26, v33
	v_lshlrev_b32_e32 v0, 16, v7
	v_and_b32_e32 v1, 0xffff0000, v7
	v_pk_fma_f32 v[0:1], v[26:27], v[2:3], v[0:1]
	v_mov_b32_e32 v24, v21
	v_mov_b32_e32 v21, v4
	v_mov_b32_e32 v25, v5
	v_mov_b32_e32 v26, v23
	v_mov_b32_e32 v23, v0
	v_mov_b32_e32 v27, v1
	s_cbranch_scc0 .LBB0_1682
	v_add_u32_e32 v28, s3, v28
	v_cmp_lt_i32_e32 vcc, s16, v28
	s_or_b64 s[8:9], vcc, s[8:9]
	v_add_u16_e32 v29, s3, v29
	s_andn2_b64 exec, exec, s[8:9]
	s_cbranch_execnz .LBB0_1681
